# w_in epilogue q/k rope tiles: rope-table rows prefetched (row blocks 0-3 kept for both column passes, 4-7 pipelined one block ahead with counted waits) instead of load+vmcnt(0) per block
# baseline (speedup 1.0000x reference)
;     __device__ __forceinline__ void operator()(const f32x4 (&acc)[2][2][4][2], const Unit& u, int wr, int wc, int fr, int fq) const {
;         const int row0 = u.pm * BM + wr * 64 + fr; const int b = (u.pm * BM) >> 12;
;         ssq_t sv[8]; float rsv[8];
; #pragma unroll
;         for (int i = 0; i < 8; ++i) sv[i] = ssqx[row0 + (i >> 2) * HALF + (i & 3) * 16];
;     ...
;                         const float* tp = (mode == 1) ? (ropA + ((size_t)row * 32 + ((col0 & 63) >> 1)) * 2) : (ropB + ((size_t)row * 16 + ((col0 - PC_KR) >> 1)) * 2);
;                         const f32x4 c0 = *(const f32x4*)tp, c1 = *(const f32x4*)(tp + 4);
.LBB0_425:
	s_lshl_b32 s2, s12, 8
	v_mbcnt_lo_u32_b32 v0, -1, 0
	v_mbcnt_hi_u32_b32 v0, -1, v0
	s_add_i32 s2, s2, s83
	v_and_b32_e32 v203, 15, v0
	v_or_b32_e32 v152, s2, v203
	v_ashrrev_i32_e32 v153, 31, v152
	v_lshl_add_u64 v[86:87], v[152:153], 3, s[28:29]
	global_load_dwordx2 v[88:89], v[86:87], off
	global_load_dwordx2 v[170:171], v[86:87], off offset:128
	global_load_dwordx2 v[168:169], v[86:87], off offset:256
	global_load_dwordx2 v[166:167], v[86:87], off offset:384
	global_load_dwordx2 v[164:165], v[86:87], off offset:1024
	global_load_dwordx2 v[162:163], v[86:87], off offset:1152
	global_load_dwordx2 v[160:161], v[86:87], off offset:1280
	global_load_dwordx2 v[158:159], v[86:87], off offset:1408
	s_lshl_b32 s32, s10, 8
	s_cmpk_lt_u32 s32, 0x200
	s_cselect_b64 s[98:99], -1, 0
	s_cbranch_scc0 .Lp2r_skip
	v_mbcnt_lo_u32_b32 v250, -1, 0
	v_mbcnt_hi_u32_b32 v250, -1, v250
	v_bfe_u32 v250, v250, 4, 2
	v_lshlrev_b32_e32 v250, 3, v250
	s_or_b32 s32, s32, s66
	v_or_b32_e32 v250, s32, v250
	v_and_b32_e32 v250, 56, v250
	v_lshlrev_b32_e32 v250, 2, v250
	v_lshl_add_u32 v220, v152, 8, v250
	global_load_dwordx4 v[186:189], v220, s[24:25]
	global_load_dwordx4 v[190:193], v220, s[24:25] offset:16
	v_add_u32_e32 v250, 0x1000, v220
	global_load_dwordx4 v[208:211], v250, s[24:25]
	global_load_dwordx4 v[212:215], v250, s[24:25] offset:16
	v_add_u32_e32 v250, 0x2000, v220
	global_load_dwordx4 v[216:219], v250, s[24:25]
	global_load_dwordx4 v[228:231], v250, s[24:25] offset:16
	v_add_u32_e32 v250, 0x3000, v220
	global_load_dwordx4 v[232:235], v250, s[24:25]
	global_load_dwordx4 v[236:239], v250, s[24:25] offset:16
; __device__ __forceinline__ float ssq_val(ssq_t v) { return (float)v * SSQ_IFX; }
;     __device__ __forceinline__ void operator()(const f32x4 (&acc)[2][2][4][2], const Unit& u, int wr, int wc, int fr, int fq) const {
;     ...
;         for (int i = 0; i < 8; ++i) sv[i] = ssqx[row0 + (i >> 2) * HALF + (i & 3) * 16];
; #pragma unroll
;         for (int i = 0; i < 8; ++i) rsv[i] = 1.0f / sqrtf(ssq_val(sv[i]) * (1.0f / DM) + EPS);
; #pragma unroll
;         for (int bj = 0; bj < 2; ++bj) {
;             const int colw = u.pn * BM + bj * HALF + wc * 32, col0 = colw + 8 * fq;
;             const int mode = colw < 512 ? 1 : (colw < 640 ? 0 : (colw < 672 ? 2 : (colw < 1536 ? 0 : 3)));
;             const int stat = (colw >= PC_CQ && colw < PC_CKV) ? 1 : ((colw >= PC_CKV && colw < PC_CKV + 256) ? 2 : 0);
;             const float sc = colw < 384 ? QS_A : 1.f;
;             const f32x4 s0 = *(const f32x4*)(shw + (size_t)b * 7680 + col0), s1 = *(const f32x4*)(shw + (size_t)b * 7680 + col0 + 4);
; #pragma unroll
;             for (int ai = 0; ai < 2; ++ai)
; #pragma unroll
;                 for (int m = 0; m < 4; ++m) {
;                     const int row = row0 + ai * HALF + m * 16;
;                     const float rs = rsv[ai * 4 + m];
;                     f32x4 v0 = acc[ai][bj][m][0] * rs + s0, v1 = acc[ai][bj][m][1] * rs + s1;
;                     if (mode == 1 || mode == 2) {
;                         const float* tp = (mode == 1) ? (ropA + ((size_t)row * 32 + ((col0 & 63) >> 1)) * 2) : (ropB + ((size_t)row * 16 + ((col0 - PC_KR) >> 1)) * 2);
;                         const f32x4 c0 = *(const f32x4*)tp, c1 = *(const f32x4*)(tp + 4);
;                         f32x4 w0, w1;
;                         w0[0] = v0[0] * c0[0] - v0[1] * c0[1]; w0[1] = v0[1] * c0[0] + v0[0] * c0[1];
;                         w0[2] = v0[2] * c0[2] - v0[3] * c0[3]; w0[3] = v0[3] * c0[2] + v0[2] * c0[3];
;                         w1[0] = v1[0] * c1[0] - v1[1] * c1[1]; w1[1] = v1[1] * c1[0] + v1[0] * c1[1];
;                         w1[2] = v1[2] * c1[2] - v1[3] * c1[3]; w1[3] = v1[3] * c1[2] + v1[2] * c1[3];
;                         v0 = w0 * sc; v1 = w1 * sc;
;                     } else if (mode == 3) {
;                         const f32x2 a = gelu_pk((f32x2){v0[0], v0[1]}), bb = gelu_pk((f32x2){v0[2], v0[3]}), c = gelu_pk((f32x2){v1[0], v1[1]}), d = gelu_pk((f32x2){v1[2], v1[3]});
.Lp2r_skip:
	v_bfe_u32 v202, v0, 4, 2
	s_lshl_b32 s35, s10, 8
	s_waitcnt vmcnt(0) lgkmcnt(0)
	v_ffbh_u32_e32 v0, v89
	v_min_u32_e32 v0, 32, v0
	v_lshlrev_b64 v[86:87], v0, v[88:89]
	v_min_u32_e32 v86, 1, v86
	v_or_b32_e32 v86, v87, v86
	v_cvt_f32_u32_e32 v86, v86
	v_sub_u32_e32 v0, 32, v0
	v_ldexp_f32 v0, v86, v0
	v_mul_f32_e32 v0, 0x33800000, v0
	v_fmamk_f32 v0, v0, 0x3a800000, v226
	s_ashr_i32 s2, s12, 4
	s_mul_hi_i32 s3, s2, 0x7800
	s_mul_i32 s11, s2, 0x7800
	s_or_b32 s2, s35, s66
	s_cmpk_lt_u32 s35, 0x600
	s_cselect_b32 s37, 0, 3
	s_cmpk_gt_u32 s2, 0x29f
	s_cselect_b32 s4, s37, 2
	s_cmpk_gt_u32 s35, 0x27f
	s_cselect_b32 s8, s4, 0
	s_cmpk_gt_i32 s2, 0x1ff
	s_cselect_b64 s[16:17], -1, 0
	s_and_b64 s[4:5], s[16:17], exec
	v_rsq_f32_e32 v154, v0
	s_nop 0
	v_lshlrev_b32_e32 v0, 3, v202
	s_cselect_b32 s4, s8, 1
	s_cmpk_lt_i32 s2, 0x180
	v_or_b32_e32 v156, s2, v0
	s_cselect_b64 s[8:9], -1, 0
	s_add_u32 s86, s96, s11
	s_addc_u32 s87, s97, s3
	v_ashrrev_i32_e32 v157, 31, v156
	v_lshl_add_u64 v[90:91], v[156:157], 2, s[86:87]
	global_load_dwordx4 v[86:89], v[90:91], off
	s_nop 0
	global_load_dwordx4 v[90:93], v[90:91], off offset:16
	s_add_i32 s3, s4, -1
	s_cmp_gt_u32 s3, 1
	s_cselect_b64 s[18:19], -1, 0
	s_cmp_eq_u32 s4, 3
	s_cselect_b64 s[10:11], -1, 0
	s_mov_b64 s[4:5], -1
	s_and_b64 vcc, exec, s[18:19]
	s_waitcnt vmcnt(0) lgkmcnt(0)
	v_pk_fma_f32 v[176:177], v[140:141], v[154:155], v[88:89] op_sel_hi:[1,0,1]
	v_pk_fma_f32 v[174:175], v[136:137], v[154:155], v[92:93] op_sel_hi:[1,0,1]
	v_cndmask_b32_e64 v136, 0, 1, s[10:11]
	v_pk_fma_f32 v[194:195], v[138:139], v[154:155], v[86:87] op_sel_hi:[1,0,1]
	v_pk_fma_f32 v[134:135], v[134:135], v[154:155], v[90:91] op_sel_hi:[1,0,1]
	v_cmp_ne_u32_e64 s[10:11], 1, v136
	s_cbranch_vccz .LBB0_429
	s_and_b64 vcc, exec, s[10:11]
	v_mov_b32_e32 v173, v177
	v_mov_b32_e32 v172, v176
	v_mov_b32_e32 v141, v195
	v_mov_b32_e32 v140, v194
	v_mov_b32_e32 v199, v175
	v_mov_b32_e32 v198, v174
	v_mov_b32_e32 v197, v135
	v_mov_b32_e32 v196, v134
	s_cbranch_vccnz .LBB0_428
	v_and_b32_e32 v137, 0x7fffffff, v195
	v_and_b32_e32 v136, 0x7fffffff, v194
	v_pk_fma_f32 v[136:137], v[136:137], s[62:63], 1.0 op_sel_hi:[1,0,0]
	s_mov_b32 s4, 0xbf3a00e3
	v_rcp_f32_e32 v136, v136
	v_rcp_f32_e32 v137, v137
	v_mov_b64_e32 v[138:139], s[4:5]
	v_cmp_gt_f32_e32 vcc, 0, v194
	v_pk_mul_f32 v[172:173], v[176:177], v[176:177]
	v_pk_fma_f32 v[140:141], v[136:137], s[64:65], v[138:139] op_sel_hi:[1,0,0]
	v_pk_mul_f32 v[172:173], v[172:173], s[74:75] op_sel_hi:[1,0]
	v_pk_fma_f32 v[140:141], v[136:137], v[140:141], s[68:69] op_sel_hi:[1,1,0]
	v_exp_f32_e32 v172, v172
	v_pk_fma_f32 v[140:141], v[136:137], v[140:141], s[70:71] op_sel_hi:[1,1,0]
	v_exp_f32_e32 v173, v173
	v_pk_fma_f32 v[140:141], v[136:137], v[140:141], s[72:73] op_sel_hi:[1,1,0]
	v_pk_mul_f32 v[180:181], v[134:135], v[134:135]
	v_pk_mul_f32 v[136:137], v[136:137], v[140:141]
	v_pk_mul_f32 v[140:141], v[194:195], v[194:195]
	v_pk_mul_f32 v[180:181], v[180:181], s[74:75] op_sel_hi:[1,0]
	v_pk_mul_f32 v[140:141], v[140:141], s[74:75] op_sel_hi:[1,0]
	v_exp_f32_e32 v180, v180
	v_exp_f32_e32 v140, v140
	v_exp_f32_e32 v141, v141
	v_exp_f32_e32 v181, v181
	v_pk_mul_f32 v[136:137], v[140:141], v[136:137]
	s_nop 0
	v_pk_mul_f32 v[140:141], v[194:195], v[136:137]
	v_pk_fma_f32 v[136:137], v[194:195], v[136:137], v[194:195] neg_lo:[1,0,0] neg_hi:[1,0,0]
	s_nop 0
	v_cndmask_b32_e32 v140, v136, v140, vcc
	v_cmp_gt_f32_e32 vcc, 0, v195
	v_and_b32_e32 v136, 0x7fffffff, v176
	s_nop 0
	v_cndmask_b32_e32 v141, v137, v141, vcc
	v_and_b32_e32 v137, 0x7fffffff, v177
	v_pk_fma_f32 v[136:137], v[136:137], s[62:63], 1.0 op_sel_hi:[1,0,0]
	v_cmp_gt_f32_e32 vcc, 0, v176
	v_rcp_f32_e32 v136, v136
	v_rcp_f32_e32 v137, v137
	s_nop 0
	v_pk_fma_f32 v[178:179], v[136:137], s[64:65], v[138:139] op_sel_hi:[1,0,0]
	s_nop 0
	v_pk_fma_f32 v[178:179], v[136:137], v[178:179], s[68:69] op_sel_hi:[1,1,0]
	s_nop 0
	v_pk_fma_f32 v[178:179], v[136:137], v[178:179], s[70:71] op_sel_hi:[1,1,0]
	s_nop 0
	v_pk_fma_f32 v[178:179], v[136:137], v[178:179], s[72:73] op_sel_hi:[1,1,0]
	s_nop 0
	v_pk_mul_f32 v[136:137], v[136:137], v[178:179]
	s_nop 0
	v_pk_mul_f32 v[136:137], v[172:173], v[136:137]
	s_nop 0
	v_pk_mul_f32 v[172:173], v[176:177], v[136:137]
	v_pk_fma_f32 v[136:137], v[176:177], v[136:137], v[176:177] neg_lo:[1,0,0] neg_hi:[1,0,0]
	s_nop 0
	v_cndmask_b32_e32 v172, v136, v172, vcc
	v_cmp_gt_f32_e32 vcc, 0, v177
	v_and_b32_e32 v136, 0x7fffffff, v134
	s_nop 0
	v_cndmask_b32_e32 v173, v137, v173, vcc
	v_and_b32_e32 v137, 0x7fffffff, v135
	v_pk_fma_f32 v[136:137], v[136:137], s[62:63], 1.0 op_sel_hi:[1,0,0]
	v_cmp_gt_f32_e32 vcc, 0, v134
	v_rcp_f32_e32 v136, v136
	v_rcp_f32_e32 v137, v137
	s_nop 0
	v_pk_fma_f32 v[178:179], v[136:137], s[64:65], v[138:139] op_sel_hi:[1,0,0]
	s_nop 0
	v_pk_fma_f32 v[178:179], v[136:137], v[178:179], s[68:69] op_sel_hi:[1,1,0]
	s_nop 0
	v_pk_fma_f32 v[178:179], v[136:137], v[178:179], s[70:71] op_sel_hi:[1,1,0]
	s_nop 0
	v_pk_fma_f32 v[178:179], v[136:137], v[178:179], s[72:73] op_sel_hi:[1,1,0]
	s_nop 0
	v_pk_mul_f32 v[136:137], v[136:137], v[178:179]
	v_pk_mul_f32 v[178:179], v[174:175], v[174:175]
	v_pk_mul_f32 v[136:137], v[180:181], v[136:137]
	s_nop 0
	v_pk_mul_f32 v[180:181], v[134:135], v[136:137]
	v_pk_fma_f32 v[136:137], v[134:135], v[136:137], v[134:135] neg_lo:[1,0,0] neg_hi:[1,0,0]
	s_nop 0
	v_cndmask_b32_e32 v196, v136, v180, vcc
	v_cmp_gt_f32_e32 vcc, 0, v135
	v_and_b32_e32 v136, 0x7fffffff, v174
	s_nop 0
	v_cndmask_b32_e32 v197, v137, v181, vcc
	v_and_b32_e32 v137, 0x7fffffff, v175
	v_pk_fma_f32 v[136:137], v[136:137], s[62:63], 1.0 op_sel_hi:[1,0,0]
	v_cmp_gt_f32_e32 vcc, 0, v174
	v_rcp_f32_e32 v136, v136
	v_rcp_f32_e32 v137, v137
	s_nop 0
	v_pk_fma_f32 v[138:139], v[136:137], s[64:65], v[138:139] op_sel_hi:[1,0,0]
	s_nop 0
	v_pk_fma_f32 v[138:139], v[136:137], v[138:139], s[68:69] op_sel_hi:[1,1,0]
	s_nop 0
	v_pk_fma_f32 v[138:139], v[136:137], v[138:139], s[70:71] op_sel_hi:[1,1,0]
	s_nop 0
	v_pk_fma_f32 v[138:139], v[136:137], v[138:139], s[72:73] op_sel_hi:[1,1,0]
	s_nop 0
	v_pk_mul_f32 v[136:137], v[136:137], v[138:139]
	v_pk_mul_f32 v[138:139], v[178:179], s[74:75] op_sel_hi:[1,0]
	s_nop 0
	v_exp_f32_e32 v138, v138
	v_exp_f32_e32 v139, v139
	s_nop 0
	v_pk_mul_f32 v[136:137], v[138:139], v[136:137]
	s_nop 0
	v_pk_mul_f32 v[138:139], v[174:175], v[136:137]
	v_pk_fma_f32 v[136:137], v[174:175], v[136:137], v[174:175] neg_lo:[1,0,0] neg_hi:[1,0,0]
	s_nop 0
	v_cndmask_b32_e32 v198, v136, v138, vcc
	v_cmp_gt_f32_e32 vcc, 0, v175
	s_nop 1
	v_cndmask_b32_e32 v199, v137, v139, vcc

;     __device__ __forceinline__ void operator()(const f32x4 (&acc)[2][2][4][2], const Unit& u, int wr, int wc, int fr, int fq) const {
;     ...
;                     f32x4 v0 = acc[ai][bj][m][0] * rs + s0, v1 = acc[ai][bj][m][1] * rs + s1;
;                     if (mode == 1 || mode == 2) {
;                         const float* tp = (mode == 1) ? (ropA + ((size_t)row * 32 + ((col0 & 63) >> 1)) * 2) : (ropB + ((size_t)row * 16 + ((col0 - PC_KR) >> 1)) * 2);
;                         const f32x4 c0 = *(const f32x4*)tp, c1 = *(const f32x4*)(tp + 4);
;                         f32x4 w0, w1;
;                         w0[0] = v0[0] * c0[0] - v0[1] * c0[1]; w0[1] = v0[1] * c0[0] + v0[0] * c0[1];
;                         w0[2] = v0[2] * c0[2] - v0[3] * c0[3]; w0[3] = v0[3] * c0[2] + v0[2] * c0[3];
;                         w1[0] = v1[0] * c1[0] - v1[1] * c1[1]; w1[1] = v1[1] * c1[0] + v1[0] * c1[1];
;                         w1[2] = v1[2] * c1[2] - v1[3] * c1[3]; w1[3] = v1[3] * c1[2] + v1[2] * c1[3];
;                         v0 = w0 * sc; v1 = w1 * sc;
.LBB0_434:
	s_and_b64 vcc, exec, s[98:99]
	s_cbranch_vccnz .Lp2r_pf_0
	global_load_dwordx4 v[196:199], v[140:141], off
	global_load_dwordx4 v[204:207], v[140:141], off offset:16
	s_waitcnt vmcnt(0) lgkmcnt(0)
	s_branch .Lp2r_done_0
.Lp2r_pf_0:
	s_waitcnt lgkmcnt(0)
	v_mov_b64_e32 v[196:197], v[186:187]
	v_mov_b64_e32 v[198:199], v[188:189]
	v_mov_b64_e32 v[204:205], v[190:191]
	v_mov_b64_e32 v[206:207], v[192:193]
.Lp2r_done_0:
	v_pk_mul_f32 v[140:141], v[194:195], v[196:197] op_sel:[1,1] op_sel_hi:[0,1]
	v_pk_fma_f32 v[178:179], v[194:195], v[196:197], v[140:141] op_sel_hi:[1,0,1] neg_lo:[0,0,1] neg_hi:[0,0,1]
	v_pk_fma_f32 v[140:141], v[194:195], v[196:197], v[140:141] op_sel_hi:[1,0,1]
	s_nop 0
	v_mov_b32_e32 v140, v199
	v_pk_mul_f32 v[172:173], v[176:177], v[140:141] op_sel:[1,0] op_sel_hi:[0,0]
	v_pk_fma_f32 v[180:181], v[176:177], v[198:199], v[172:173] op_sel_hi:[1,0,1] neg_lo:[0,0,1] neg_hi:[0,0,1]
	v_pk_fma_f32 v[172:173], v[176:177], v[198:199], v[172:173] op_sel_hi:[1,0,1]
	v_pk_mul_f32 v[176:177], v[134:135], v[204:205] op_sel:[1,1] op_sel_hi:[0,1]
	v_pk_fma_f32 v[182:183], v[134:135], v[204:205], v[176:177] op_sel_hi:[1,0,1] neg_lo:[0,0,1] neg_hi:[0,0,1]
	v_pk_fma_f32 v[134:135], v[134:135], v[204:205], v[176:177] op_sel_hi:[1,0,1]
	v_mov_b32_e32 v181, v173
	v_mov_b32_e32 v134, v207
	v_pk_mul_f32 v[176:177], v[174:175], v[134:135] op_sel:[1,0] op_sel_hi:[0,0]
	v_pk_fma_f32 v[184:185], v[174:175], v[206:207], v[176:177] op_sel_hi:[1,0,1] neg_lo:[0,0,1] neg_hi:[0,0,1]
	v_pk_fma_f32 v[174:175], v[174:175], v[206:207], v[176:177] op_sel_hi:[1,0,1]
	v_mov_b32_e32 v176, v136
	v_mov_b32_e32 v177, v136
	v_mov_b32_e32 v179, v141
	v_mov_b32_e32 v185, v175
	v_mov_b32_e32 v183, v135
	v_pk_mul_f32 v[172:173], v[176:177], v[180:181]
	v_pk_mul_f32 v[140:141], v[136:137], v[178:179]
	v_pk_mul_f32 v[198:199], v[176:177], v[184:185]
	v_pk_mul_f32 v[196:197], v[136:137], v[182:183]

;     __device__ __forceinline__ void operator()(const f32x4 (&acc)[2][2][4][2], const Unit& u, int wr, int wc, int fr, int fq) const {
;     ...
;                     f32x4 v0 = acc[ai][bj][m][0] * rs + s0, v1 = acc[ai][bj][m][1] * rs + s1;
;                     if (mode == 1 || mode == 2) {
;                         const float* tp = (mode == 1) ? (ropA + ((size_t)row * 32 + ((col0 & 63) >> 1)) * 2) : (ropB + ((size_t)row * 16 + ((col0 - PC_KR) >> 1)) * 2);
;                         const f32x4 c0 = *(const f32x4*)tp, c1 = *(const f32x4*)(tp + 4);
;                         f32x4 w0, w1;
;                         w0[0] = v0[0] * c0[0] - v0[1] * c0[1]; w0[1] = v0[1] * c0[0] + v0[0] * c0[1];
;                         w0[2] = v0[2] * c0[2] - v0[3] * c0[3]; w0[3] = v0[3] * c0[2] + v0[2] * c0[3];
;                         w1[0] = v1[0] * c1[0] - v1[1] * c1[1]; w1[1] = v1[1] * c1[0] + v1[0] * c1[1];
;                         w1[2] = v1[2] * c1[2] - v1[3] * c1[3]; w1[3] = v1[3] * c1[2] + v1[2] * c1[3];
;                         v0 = w0 * sc; v1 = w1 * sc;
.LBB0_448:
	s_and_b64 vcc, exec, s[98:99]
	s_cbranch_vccnz .Lp2r_pf_1
	global_load_dwordx4 v[174:177], v[130:131], off
	s_nop 0
	global_load_dwordx4 v[130:133], v[130:131], off offset:16
	s_waitcnt vmcnt(0) lgkmcnt(0)
	s_branch .Lp2r_done_1
.Lp2r_pf_1:
	s_waitcnt lgkmcnt(0)
	v_mov_b64_e32 v[174:175], v[208:209]
	v_mov_b64_e32 v[176:177], v[210:211]
	v_mov_b64_e32 v[130:131], v[212:213]
	v_mov_b64_e32 v[132:133], v[214:215]
.Lp2r_done_1:
	v_pk_mul_f32 v[178:179], v[170:171], v[174:175] op_sel:[1,1] op_sel_hi:[0,1]
	v_pk_fma_f32 v[180:181], v[170:171], v[174:175], v[178:179] op_sel_hi:[1,0,1] neg_lo:[0,0,1] neg_hi:[0,0,1]
	v_pk_fma_f32 v[170:171], v[170:171], v[174:175], v[178:179] op_sel_hi:[1,0,1]
	s_nop 0
	v_mov_b32_e32 v170, v177
	v_pk_mul_f32 v[174:175], v[140:141], v[170:171] op_sel:[1,0] op_sel_hi:[0,0]
	v_pk_fma_f32 v[178:179], v[140:141], v[176:177], v[174:175] op_sel_hi:[1,0,1] neg_lo:[0,0,1] neg_hi:[0,0,1]
	v_pk_fma_f32 v[140:141], v[140:141], v[176:177], v[174:175] op_sel_hi:[1,0,1]
	v_pk_mul_f32 v[174:175], v[172:173], v[130:131] op_sel:[1,1] op_sel_hi:[0,1]
	v_pk_fma_f32 v[182:183], v[172:173], v[130:131], v[174:175] op_sel_hi:[1,0,1] neg_lo:[0,0,1] neg_hi:[0,0,1]
	v_pk_fma_f32 v[172:173], v[172:173], v[130:131], v[174:175] op_sel_hi:[1,0,1]
	v_mov_b32_e32 v130, v133
	v_pk_mul_f32 v[130:131], v[128:129], v[130:131] op_sel:[1,0] op_sel_hi:[0,0]
	v_pk_fma_f32 v[174:175], v[128:129], v[132:133], v[130:131] op_sel_hi:[1,0,1] neg_lo:[0,0,1] neg_hi:[0,0,1]
	v_pk_fma_f32 v[128:129], v[128:129], v[132:133], v[130:131] op_sel_hi:[1,0,1]
	v_mov_b32_e32 v179, v141
	v_mov_b32_e32 v140, v136
	v_mov_b32_e32 v141, v136
	v_mov_b32_e32 v181, v171
	v_mov_b32_e32 v175, v129
	v_mov_b32_e32 v183, v173
	v_pk_mul_f32 v[132:133], v[140:141], v[178:179]
	v_pk_mul_f32 v[130:131], v[136:137], v[180:181]
	v_pk_mul_f32 v[176:177], v[140:141], v[174:175]
	v_pk_mul_f32 v[174:175], v[136:137], v[182:183]

;     __device__ __forceinline__ void operator()(const f32x4 (&acc)[2][2][4][2], const Unit& u, int wr, int wc, int fr, int fq) const {
;     ...
;                     f32x4 v0 = acc[ai][bj][m][0] * rs + s0, v1 = acc[ai][bj][m][1] * rs + s1;
;                     if (mode == 1 || mode == 2) {
;                         const float* tp = (mode == 1) ? (ropA + ((size_t)row * 32 + ((col0 & 63) >> 1)) * 2) : (ropB + ((size_t)row * 16 + ((col0 - PC_KR) >> 1)) * 2);
;                         const f32x4 c0 = *(const f32x4*)tp, c1 = *(const f32x4*)(tp + 4);
;                         f32x4 w0, w1;
;                         w0[0] = v0[0] * c0[0] - v0[1] * c0[1]; w0[1] = v0[1] * c0[0] + v0[0] * c0[1];
;                         w0[2] = v0[2] * c0[2] - v0[3] * c0[3]; w0[3] = v0[3] * c0[2] + v0[2] * c0[3];
;                         w1[0] = v1[0] * c1[0] - v1[1] * c1[1]; w1[1] = v1[1] * c1[0] + v1[0] * c1[1];
;                         w1[2] = v1[2] * c1[2] - v1[3] * c1[3]; w1[3] = v1[3] * c1[2] + v1[2] * c1[3];
;                         v0 = w0 * sc; v1 = w1 * sc;
.LBB0_463:
	s_and_b64 vcc, exec, s[98:99]
	s_cbranch_vccnz .Lp2r_pf_2
	global_load_dwordx4 v[168:171], v[122:123], off
	s_nop 0
	global_load_dwordx4 v[122:125], v[122:123], off offset:16
	s_waitcnt vmcnt(0) lgkmcnt(0)
	s_branch .Lp2r_done_2
.Lp2r_pf_2:
	s_waitcnt lgkmcnt(0)
	v_mov_b64_e32 v[168:169], v[216:217]
	v_mov_b64_e32 v[170:171], v[218:219]
	v_mov_b64_e32 v[122:123], v[228:229]
	v_mov_b64_e32 v[124:125], v[230:231]
.Lp2r_done_2:
	v_pk_mul_f32 v[174:175], v[132:133], v[168:169] op_sel:[1,1] op_sel_hi:[0,1]
	v_pk_fma_f32 v[176:177], v[132:133], v[168:169], v[174:175] op_sel_hi:[1,0,1] neg_lo:[0,0,1] neg_hi:[0,0,1]
	v_pk_fma_f32 v[132:133], v[132:133], v[168:169], v[174:175] op_sel_hi:[1,0,1]
	s_nop 0
	v_mov_b32_e32 v132, v171
	v_pk_mul_f32 v[168:169], v[130:131], v[132:133] op_sel:[1,0] op_sel_hi:[0,0]
	v_pk_fma_f32 v[174:175], v[130:131], v[170:171], v[168:169] op_sel_hi:[1,0,1] neg_lo:[0,0,1] neg_hi:[0,0,1]
	v_pk_fma_f32 v[130:131], v[130:131], v[170:171], v[168:169] op_sel_hi:[1,0,1]
	v_pk_mul_f32 v[168:169], v[140:141], v[122:123] op_sel:[1,1] op_sel_hi:[0,1]
	v_pk_fma_f32 v[178:179], v[140:141], v[122:123], v[168:169] op_sel_hi:[1,0,1] neg_lo:[0,0,1] neg_hi:[0,0,1]
	v_pk_fma_f32 v[140:141], v[140:141], v[122:123], v[168:169] op_sel_hi:[1,0,1]
	v_mov_b32_e32 v122, v125
	v_pk_mul_f32 v[122:123], v[120:121], v[122:123] op_sel:[1,0] op_sel_hi:[0,0]
	v_pk_fma_f32 v[168:169], v[120:121], v[124:125], v[122:123] op_sel_hi:[1,0,1] neg_lo:[0,0,1] neg_hi:[0,0,1]
	v_pk_fma_f32 v[120:121], v[120:121], v[124:125], v[122:123] op_sel_hi:[1,0,1]
	v_mov_b32_e32 v175, v131
	v_mov_b32_e32 v130, v136
	v_mov_b32_e32 v131, v136
	v_mov_b32_e32 v177, v133
	v_mov_b32_e32 v169, v121
	v_mov_b32_e32 v179, v141
	v_pk_mul_f32 v[124:125], v[130:131], v[174:175]
	v_pk_mul_f32 v[122:123], v[136:137], v[176:177]
	v_pk_mul_f32 v[170:171], v[130:131], v[168:169]
	v_pk_mul_f32 v[168:169], v[136:137], v[178:179]
	v_mov_b32_e32 v129, v128
	s_and_b64 vcc, exec, s[16:17]
	s_cbranch_vccnz .LBB0_467

;     __device__ __forceinline__ void operator()(const f32x4 (&acc)[2][2][4][2], const Unit& u, int wr, int wc, int fr, int fq) const {
;     ...
;                     f32x4 v0 = acc[ai][bj][m][0] * rs + s0, v1 = acc[ai][bj][m][1] * rs + s1;
;                     if (mode == 1 || mode == 2) {
;                         const float* tp = (mode == 1) ? (ropA + ((size_t)row * 32 + ((col0 & 63) >> 1)) * 2) : (ropB + ((size_t)row * 16 + ((col0 - PC_KR) >> 1)) * 2);
;                         const f32x4 c0 = *(const f32x4*)tp, c1 = *(const f32x4*)(tp + 4);
;                         f32x4 w0, w1;
;                         w0[0] = v0[0] * c0[0] - v0[1] * c0[1]; w0[1] = v0[1] * c0[0] + v0[0] * c0[1];
;                         w0[2] = v0[2] * c0[2] - v0[3] * c0[3]; w0[3] = v0[3] * c0[2] + v0[2] * c0[3];
;                         w1[0] = v1[0] * c1[0] - v1[1] * c1[1]; w1[1] = v1[1] * c1[0] + v1[0] * c1[1];
;                         w1[2] = v1[2] * c1[2] - v1[3] * c1[3]; w1[3] = v1[3] * c1[2] + v1[2] * c1[3];
;                         v0 = w0 * sc; v1 = w1 * sc;
.LBB0_477:
	s_and_b64 vcc, exec, s[98:99]
	s_cbranch_vccnz .Lp2r_pf_3
	global_load_dwordx4 v[168:171], v[114:115], off
	s_nop 0
	global_load_dwordx4 v[114:117], v[114:115], off offset:16
	s_waitcnt vmcnt(0) lgkmcnt(0)
	s_branch .Lp2r_done_3
.Lp2r_pf_3:
	s_waitcnt lgkmcnt(0)
	v_mov_b64_e32 v[168:169], v[232:233]
	v_mov_b64_e32 v[170:171], v[234:235]
	v_mov_b64_e32 v[114:115], v[236:237]
	v_mov_b64_e32 v[116:117], v[238:239]
	v_add_u32_e32 v250, 0x8000, v220
	global_load_dwordx4 v[240:243], v250, s[24:25]
	global_load_dwordx4 v[244:247], v250, s[24:25] offset:16
.Lp2r_done_3:
	v_pk_mul_f32 v[132:133], v[124:125], v[168:169] op_sel:[1,1] op_sel_hi:[0,1]
	v_pk_fma_f32 v[140:141], v[124:125], v[168:169], v[132:133] op_sel_hi:[1,0,1] neg_lo:[0,0,1] neg_hi:[0,0,1]
	v_pk_fma_f32 v[124:125], v[124:125], v[168:169], v[132:133] op_sel_hi:[1,0,1]
	s_nop 0
	v_mov_b32_e32 v124, v171
	v_pk_mul_f32 v[132:133], v[122:123], v[124:125] op_sel:[1,0] op_sel_hi:[0,0]
	v_pk_fma_f32 v[168:169], v[122:123], v[170:171], v[132:133] op_sel_hi:[1,0,1] neg_lo:[0,0,1] neg_hi:[0,0,1]
	v_pk_fma_f32 v[122:123], v[122:123], v[170:171], v[132:133] op_sel_hi:[1,0,1]
	v_pk_mul_f32 v[132:133], v[130:131], v[114:115] op_sel:[1,1] op_sel_hi:[0,1]
	v_pk_fma_f32 v[170:171], v[130:131], v[114:115], v[132:133] op_sel_hi:[1,0,1] neg_lo:[0,0,1] neg_hi:[0,0,1]
	v_pk_fma_f32 v[130:131], v[130:131], v[114:115], v[132:133] op_sel_hi:[1,0,1]
	v_mov_b32_e32 v114, v117
	v_pk_mul_f32 v[114:115], v[112:113], v[114:115] op_sel:[1,0] op_sel_hi:[0,0]
	v_pk_fma_f32 v[132:133], v[112:113], v[116:117], v[114:115] op_sel_hi:[1,0,1] neg_lo:[0,0,1] neg_hi:[0,0,1]
	v_pk_fma_f32 v[112:113], v[112:113], v[116:117], v[114:115] op_sel_hi:[1,0,1]
	v_mov_b32_e32 v169, v123
	v_mov_b32_e32 v122, v136
	v_mov_b32_e32 v123, v136
	v_mov_b32_e32 v141, v125
	v_mov_b32_e32 v133, v113
	v_mov_b32_e32 v171, v131
	v_pk_mul_f32 v[116:117], v[122:123], v[168:169]
	v_pk_mul_f32 v[114:115], v[136:137], v[140:141]
	v_pk_mul_f32 v[140:141], v[122:123], v[132:133]
	v_pk_mul_f32 v[132:133], v[136:137], v[170:171]
	v_mov_b32_e32 v121, v120
	s_and_b64 vcc, exec, s[16:17]
	s_cbranch_vccnz .LBB0_481

;     __device__ __forceinline__ void operator()(const f32x4 (&acc)[2][2][4][2], const Unit& u, int wr, int wc, int fr, int fq) const {
;     ...
;                     f32x4 v0 = acc[ai][bj][m][0] * rs + s0, v1 = acc[ai][bj][m][1] * rs + s1;
;                     if (mode == 1 || mode == 2) {
;                         const float* tp = (mode == 1) ? (ropA + ((size_t)row * 32 + ((col0 & 63) >> 1)) * 2) : (ropB + ((size_t)row * 16 + ((col0 - PC_KR) >> 1)) * 2);
;                         const f32x4 c0 = *(const f32x4*)tp, c1 = *(const f32x4*)(tp + 4);
;                         f32x4 w0, w1;
;                         w0[0] = v0[0] * c0[0] - v0[1] * c0[1]; w0[1] = v0[1] * c0[0] + v0[0] * c0[1];
;                         w0[2] = v0[2] * c0[2] - v0[3] * c0[3]; w0[3] = v0[3] * c0[2] + v0[2] * c0[3];
;                         w1[0] = v1[0] * c1[0] - v1[1] * c1[1]; w1[1] = v1[1] * c1[0] + v1[0] * c1[1];
;                         w1[2] = v1[2] * c1[2] - v1[3] * c1[3]; w1[3] = v1[3] * c1[2] + v1[2] * c1[3];
;                         v0 = w0 * sc; v1 = w1 * sc;
.LBB0_491:
	s_and_b64 vcc, exec, s[98:99]
	s_cbranch_vccnz .Lp2r_pf_4
	global_load_dwordx4 v[168:171], v[106:107], off
	s_nop 0
	global_load_dwordx4 v[106:109], v[106:107], off offset:16
	s_waitcnt vmcnt(0) lgkmcnt(0)
	s_branch .Lp2r_done_4
.Lp2r_pf_4:
	s_waitcnt vmcnt(1) lgkmcnt(0)
	v_mov_b64_e32 v[168:169], v[240:241]
	v_mov_b64_e32 v[170:171], v[242:243]
	v_mov_b64_e32 v[106:107], v[244:245]
	v_mov_b64_e32 v[108:109], v[246:247]
	v_add_u32_e32 v250, 0x9000, v220
	global_load_dwordx4 v[240:243], v250, s[24:25]
	global_load_dwordx4 v[244:247], v250, s[24:25] offset:16
.Lp2r_done_4:
	v_pk_mul_f32 v[124:125], v[116:117], v[168:169] op_sel:[1,1] op_sel_hi:[0,1]
	v_pk_fma_f32 v[130:131], v[116:117], v[168:169], v[124:125] op_sel_hi:[1,0,1] neg_lo:[0,0,1] neg_hi:[0,0,1]
	v_pk_fma_f32 v[116:117], v[116:117], v[168:169], v[124:125] op_sel_hi:[1,0,1]
	s_nop 0
	v_mov_b32_e32 v116, v171
	v_pk_mul_f32 v[124:125], v[114:115], v[116:117] op_sel:[1,0] op_sel_hi:[0,0]
	v_pk_fma_f32 v[140:141], v[114:115], v[170:171], v[124:125] op_sel_hi:[1,0,1] neg_lo:[0,0,1] neg_hi:[0,0,1]
	v_pk_fma_f32 v[114:115], v[114:115], v[170:171], v[124:125] op_sel_hi:[1,0,1]
	v_pk_mul_f32 v[124:125], v[122:123], v[106:107] op_sel:[1,1] op_sel_hi:[0,1]
	v_pk_fma_f32 v[164:165], v[122:123], v[106:107], v[124:125] op_sel_hi:[1,0,1] neg_lo:[0,0,1] neg_hi:[0,0,1]
	v_pk_fma_f32 v[122:123], v[122:123], v[106:107], v[124:125] op_sel_hi:[1,0,1]
	v_mov_b32_e32 v106, v109
	v_pk_mul_f32 v[106:107], v[104:105], v[106:107] op_sel:[1,0] op_sel_hi:[0,0]
	v_pk_fma_f32 v[124:125], v[104:105], v[108:109], v[106:107] op_sel_hi:[1,0,1] neg_lo:[0,0,1] neg_hi:[0,0,1]
	v_pk_fma_f32 v[104:105], v[104:105], v[108:109], v[106:107] op_sel_hi:[1,0,1]
	v_mov_b32_e32 v141, v115
	v_mov_b32_e32 v114, v136
	v_mov_b32_e32 v115, v136
	v_mov_b32_e32 v131, v117
	v_mov_b32_e32 v125, v105
	v_mov_b32_e32 v165, v123
	v_pk_mul_f32 v[108:109], v[114:115], v[140:141]
	v_pk_mul_f32 v[106:107], v[136:137], v[130:131]
	v_pk_mul_f32 v[130:131], v[114:115], v[124:125]
	v_pk_mul_f32 v[124:125], v[136:137], v[164:165]
	v_mov_b32_e32 v113, v112
	s_and_b64 vcc, exec, s[16:17]
	s_cbranch_vccnz .LBB0_495

;     __device__ __forceinline__ void operator()(const f32x4 (&acc)[2][2][4][2], const Unit& u, int wr, int wc, int fr, int fq) const {
;     ...
;                     f32x4 v0 = acc[ai][bj][m][0] * rs + s0, v1 = acc[ai][bj][m][1] * rs + s1;
;                     if (mode == 1 || mode == 2) {
;                         const float* tp = (mode == 1) ? (ropA + ((size_t)row * 32 + ((col0 & 63) >> 1)) * 2) : (ropB + ((size_t)row * 16 + ((col0 - PC_KR) >> 1)) * 2);
;                         const f32x4 c0 = *(const f32x4*)tp, c1 = *(const f32x4*)(tp + 4);
;                         f32x4 w0, w1;
;                         w0[0] = v0[0] * c0[0] - v0[1] * c0[1]; w0[1] = v0[1] * c0[0] + v0[0] * c0[1];
;                         w0[2] = v0[2] * c0[2] - v0[3] * c0[3]; w0[3] = v0[3] * c0[2] + v0[2] * c0[3];
;                         w1[0] = v1[0] * c1[0] - v1[1] * c1[1]; w1[1] = v1[1] * c1[0] + v1[0] * c1[1];
;                         w1[2] = v1[2] * c1[2] - v1[3] * c1[3]; w1[3] = v1[3] * c1[2] + v1[2] * c1[3];
;                         v0 = w0 * sc; v1 = w1 * sc;
.LBB0_505:
	s_and_b64 vcc, exec, s[98:99]
	s_cbranch_vccnz .Lp2r_pf_5
	global_load_dwordx4 v[162:165], v[98:99], off
	s_nop 0
	global_load_dwordx4 v[98:101], v[98:99], off offset:16
	s_waitcnt vmcnt(0) lgkmcnt(0)
	s_branch .Lp2r_done_5
.Lp2r_pf_5:
	s_waitcnt vmcnt(1) lgkmcnt(0)
	v_mov_b64_e32 v[162:163], v[240:241]
	v_mov_b64_e32 v[164:165], v[242:243]
	v_mov_b64_e32 v[98:99], v[244:245]
	v_mov_b64_e32 v[100:101], v[246:247]
	v_add_u32_e32 v250, 0xa000, v220
	global_load_dwordx4 v[240:243], v250, s[24:25]
	global_load_dwordx4 v[244:247], v250, s[24:25] offset:16
.Lp2r_done_5:
	v_pk_mul_f32 v[116:117], v[108:109], v[162:163] op_sel:[1,1] op_sel_hi:[0,1]
	v_pk_fma_f32 v[122:123], v[108:109], v[162:163], v[116:117] op_sel_hi:[1,0,1] neg_lo:[0,0,1] neg_hi:[0,0,1]
	v_pk_fma_f32 v[108:109], v[108:109], v[162:163], v[116:117] op_sel_hi:[1,0,1]
	s_nop 0
	v_mov_b32_e32 v108, v165
	v_pk_mul_f32 v[116:117], v[106:107], v[108:109] op_sel:[1,0] op_sel_hi:[0,0]
	v_pk_fma_f32 v[130:131], v[106:107], v[164:165], v[116:117] op_sel_hi:[1,0,1] neg_lo:[0,0,1] neg_hi:[0,0,1]
	v_pk_fma_f32 v[106:107], v[106:107], v[164:165], v[116:117] op_sel_hi:[1,0,1]
	v_pk_mul_f32 v[116:117], v[114:115], v[98:99] op_sel:[1,1] op_sel_hi:[0,1]
	v_pk_fma_f32 v[140:141], v[114:115], v[98:99], v[116:117] op_sel_hi:[1,0,1] neg_lo:[0,0,1] neg_hi:[0,0,1]
	v_pk_fma_f32 v[114:115], v[114:115], v[98:99], v[116:117] op_sel_hi:[1,0,1]
	v_mov_b32_e32 v98, v101
	v_pk_mul_f32 v[98:99], v[96:97], v[98:99] op_sel:[1,0] op_sel_hi:[0,0]
	v_pk_fma_f32 v[116:117], v[96:97], v[100:101], v[98:99] op_sel_hi:[1,0,1] neg_lo:[0,0,1] neg_hi:[0,0,1]
	v_pk_fma_f32 v[96:97], v[96:97], v[100:101], v[98:99] op_sel_hi:[1,0,1]
	v_mov_b32_e32 v131, v107
	v_mov_b32_e32 v106, v136
	v_mov_b32_e32 v107, v136
	v_mov_b32_e32 v123, v109
	v_mov_b32_e32 v117, v97
	v_mov_b32_e32 v141, v115
	v_pk_mul_f32 v[100:101], v[106:107], v[130:131]
	v_pk_mul_f32 v[98:99], v[136:137], v[122:123]
	v_pk_mul_f32 v[122:123], v[106:107], v[116:117]
	v_pk_mul_f32 v[116:117], v[136:137], v[140:141]
	v_mov_b32_e32 v105, v104
	s_and_b64 vcc, exec, s[16:17]
	s_cbranch_vccnz .LBB0_509

;     __device__ __forceinline__ void operator()(const f32x4 (&acc)[2][2][4][2], const Unit& u, int wr, int wc, int fr, int fq) const {
;     ...
;                     f32x4 v0 = acc[ai][bj][m][0] * rs + s0, v1 = acc[ai][bj][m][1] * rs + s1;
;                     if (mode == 1 || mode == 2) {
;                         const float* tp = (mode == 1) ? (ropA + ((size_t)row * 32 + ((col0 & 63) >> 1)) * 2) : (ropB + ((size_t)row * 16 + ((col0 - PC_KR) >> 1)) * 2);
;                         const f32x4 c0 = *(const f32x4*)tp, c1 = *(const f32x4*)(tp + 4);
;                         f32x4 w0, w1;
;                         w0[0] = v0[0] * c0[0] - v0[1] * c0[1]; w0[1] = v0[1] * c0[0] + v0[0] * c0[1];
;                         w0[2] = v0[2] * c0[2] - v0[3] * c0[3]; w0[3] = v0[3] * c0[2] + v0[2] * c0[3];
;                         w1[0] = v1[0] * c1[0] - v1[1] * c1[1]; w1[1] = v1[1] * c1[0] + v1[0] * c1[1];
;                         w1[2] = v1[2] * c1[2] - v1[3] * c1[3]; w1[3] = v1[3] * c1[2] + v1[2] * c1[3];
;                         v0 = w0 * sc; v1 = w1 * sc;
.LBB0_519:
	s_and_b64 vcc, exec, s[98:99]
	s_cbranch_vccnz .Lp2r_pf_6
	global_load_dwordx4 v[160:163], v[80:81], off
	global_load_dwordx4 v[168:171], v[80:81], off offset:16
	s_waitcnt vmcnt(0) lgkmcnt(0)
	s_branch .Lp2r_done_6
.Lp2r_pf_6:
	s_waitcnt vmcnt(1) lgkmcnt(0)
	v_mov_b64_e32 v[160:161], v[240:241]
	v_mov_b64_e32 v[162:163], v[242:243]
	v_mov_b64_e32 v[168:169], v[244:245]
	v_mov_b64_e32 v[170:171], v[246:247]
	v_add_u32_e32 v250, 0xb000, v220
	global_load_dwordx4 v[240:243], v250, s[24:25]
	global_load_dwordx4 v[244:247], v250, s[24:25] offset:16
.Lp2r_done_6:
	v_pk_mul_f32 v[80:81], v[100:101], v[160:161] op_sel:[1,1] op_sel_hi:[0,1]
	v_pk_fma_f32 v[108:109], v[100:101], v[160:161], v[80:81] op_sel_hi:[1,0,1] neg_lo:[0,0,1] neg_hi:[0,0,1]
	v_pk_fma_f32 v[80:81], v[100:101], v[160:161], v[80:81] op_sel_hi:[1,0,1]
	s_nop 0
	v_mov_b32_e32 v80, v163
	v_pk_mul_f32 v[84:85], v[98:99], v[80:81] op_sel:[1,0] op_sel_hi:[0,0]
	v_pk_fma_f32 v[100:101], v[98:99], v[162:163], v[84:85] op_sel_hi:[1,0,1] neg_lo:[0,0,1] neg_hi:[0,0,1]
	v_pk_fma_f32 v[84:85], v[98:99], v[162:163], v[84:85] op_sel_hi:[1,0,1]
	v_pk_mul_f32 v[98:99], v[106:107], v[168:169] op_sel:[1,1] op_sel_hi:[0,1]
	v_mov_b32_e32 v80, v171
	v_pk_fma_f32 v[122:123], v[106:107], v[168:169], v[98:99] op_sel_hi:[1,0,1] neg_lo:[0,0,1] neg_hi:[0,0,1]
	v_pk_fma_f32 v[98:99], v[106:107], v[168:169], v[98:99] op_sel_hi:[1,0,1]
	v_pk_mul_f32 v[106:107], v[82:83], v[80:81] op_sel:[1,0] op_sel_hi:[0,0]
	v_pk_fma_f32 v[114:115], v[82:83], v[170:171], v[106:107] op_sel_hi:[1,0,1] neg_lo:[0,0,1] neg_hi:[0,0,1]
	v_pk_fma_f32 v[82:83], v[82:83], v[170:171], v[106:107] op_sel_hi:[1,0,1]
	v_mov_b32_e32 v101, v85
	v_mov_b32_e32 v106, v136
	v_mov_b32_e32 v107, v136
	v_mov_b32_e32 v109, v81
	v_mov_b32_e32 v115, v83
	v_mov_b32_e32 v123, v99
	v_pk_mul_f32 v[84:85], v[106:107], v[100:101]
	v_pk_mul_f32 v[80:81], v[136:137], v[108:109]
	v_pk_mul_f32 v[114:115], v[106:107], v[114:115]
	v_pk_mul_f32 v[108:109], v[136:137], v[122:123]
	v_mov_b32_e32 v97, v96
	s_and_b64 vcc, exec, s[16:17]
	s_cbranch_vccnz .LBB0_523

;     __device__ __forceinline__ void operator()(const f32x4 (&acc)[2][2][4][2], const Unit& u, int wr, int wc, int fr, int fq) const {
;     ...
;                     f32x4 v0 = acc[ai][bj][m][0] * rs + s0, v1 = acc[ai][bj][m][1] * rs + s1;
;                     if (mode == 1 || mode == 2) {
;                         const float* tp = (mode == 1) ? (ropA + ((size_t)row * 32 + ((col0 & 63) >> 1)) * 2) : (ropB + ((size_t)row * 16 + ((col0 - PC_KR) >> 1)) * 2);
;                         const f32x4 c0 = *(const f32x4*)tp, c1 = *(const f32x4*)(tp + 4);
;                         f32x4 w0, w1;
;                         w0[0] = v0[0] * c0[0] - v0[1] * c0[1]; w0[1] = v0[1] * c0[0] + v0[0] * c0[1];
;                         w0[2] = v0[2] * c0[2] - v0[3] * c0[3]; w0[3] = v0[3] * c0[2] + v0[2] * c0[3];
;                         w1[0] = v1[0] * c1[0] - v1[1] * c1[1]; w1[1] = v1[1] * c1[0] + v1[0] * c1[1];
;                         w1[2] = v1[2] * c1[2] - v1[3] * c1[3]; w1[3] = v1[3] * c1[2] + v1[2] * c1[3];
;                         v0 = w0 * sc; v1 = w1 * sc;
.LBB0_533:
	s_and_b64 vcc, exec, s[98:99]
	s_cbranch_vccnz .Lp2r_pf_7
	global_load_dwordx4 v[88:91], v[70:71], off
	s_nop 0
	global_load_dwordx4 v[70:73], v[70:71], off offset:16
	s_waitcnt vmcnt(0) lgkmcnt(0)
	s_branch .Lp2r_done_7
.Lp2r_pf_7:
	s_waitcnt vmcnt(1) lgkmcnt(0)
	v_mov_b64_e32 v[88:89], v[240:241]
	v_mov_b64_e32 v[90:91], v[242:243]
	v_mov_b64_e32 v[70:71], v[244:245]
	v_mov_b64_e32 v[72:73], v[246:247]
.Lp2r_done_7:
	v_pk_mul_f32 v[92:93], v[84:85], v[88:89] op_sel:[1,1] op_sel_hi:[0,1]
	v_pk_fma_f32 v[98:99], v[84:85], v[88:89], v[92:93] op_sel_hi:[1,0,1] neg_lo:[0,0,1] neg_hi:[0,0,1]
	v_pk_fma_f32 v[84:85], v[84:85], v[88:89], v[92:93] op_sel_hi:[1,0,1]
	s_nop 0
	v_mov_b32_e32 v84, v91
	v_pk_mul_f32 v[88:89], v[76:77], v[84:85] op_sel:[1,0] op_sel_hi:[0,0]
	v_pk_fma_f32 v[92:93], v[76:77], v[90:91], v[88:89] op_sel_hi:[1,0,1] neg_lo:[0,0,1] neg_hi:[0,0,1]
	v_pk_fma_f32 v[76:77], v[76:77], v[90:91], v[88:89] op_sel_hi:[1,0,1]
	v_pk_mul_f32 v[88:89], v[86:87], v[70:71] op_sel:[1,1] op_sel_hi:[0,1]
	v_pk_fma_f32 v[106:107], v[86:87], v[70:71], v[88:89] op_sel_hi:[1,0,1] neg_lo:[0,0,1] neg_hi:[0,0,1]
	v_pk_fma_f32 v[86:87], v[86:87], v[70:71], v[88:89] op_sel_hi:[1,0,1]
	v_mov_b32_e32 v70, v73
	v_pk_mul_f32 v[70:71], v[74:75], v[70:71] op_sel:[1,0] op_sel_hi:[0,0]
	v_pk_fma_f32 v[88:89], v[74:75], v[72:73], v[70:71] op_sel_hi:[1,0,1] neg_lo:[0,0,1] neg_hi:[0,0,1]
	v_pk_fma_f32 v[74:75], v[74:75], v[72:73], v[70:71] op_sel_hi:[1,0,1]
	v_mov_b32_e32 v93, v77
	v_mov_b32_e32 v76, v136
	v_mov_b32_e32 v77, v136
	v_mov_b32_e32 v99, v85
	v_mov_b32_e32 v89, v75
	v_mov_b32_e32 v107, v87
	v_pk_mul_f32 v[72:73], v[76:77], v[92:93]
	v_pk_mul_f32 v[70:71], v[136:137], v[98:99]
	v_pk_mul_f32 v[90:91], v[76:77], v[88:89]
	v_pk_mul_f32 v[88:89], v[136:137], v[106:107]
	v_mov_b32_e32 v83, v82
	s_and_b64 vcc, exec, s[16:17]
	s_cbranch_vccnz .LBB0_537

;     __device__ __forceinline__ void operator()(const f32x4 (&acc)[2][2][4][2], const Unit& u, int wr, int wc, int fr, int fq) const {
;     ...
;                     f32x4 v0 = acc[ai][bj][m][0] * rs + s0, v1 = acc[ai][bj][m][1] * rs + s1;
;                     if (mode == 1 || mode == 2) {
;                         const float* tp = (mode == 1) ? (ropA + ((size_t)row * 32 + ((col0 & 63) >> 1)) * 2) : (ropB + ((size_t)row * 16 + ((col0 - PC_KR) >> 1)) * 2);
;                         const f32x4 c0 = *(const f32x4*)tp, c1 = *(const f32x4*)(tp + 4);
;                         f32x4 w0, w1;
;                         w0[0] = v0[0] * c0[0] - v0[1] * c0[1]; w0[1] = v0[1] * c0[0] + v0[0] * c0[1];
;                         w0[2] = v0[2] * c0[2] - v0[3] * c0[3]; w0[3] = v0[3] * c0[2] + v0[2] * c0[3];
;                         w1[0] = v1[0] * c1[0] - v1[1] * c1[1]; w1[1] = v1[1] * c1[0] + v1[0] * c1[1];
;                         w1[2] = v1[2] * c1[2] - v1[3] * c1[3]; w1[3] = v1[3] * c1[2] + v1[2] * c1[3];
;                         v0 = w0 * sc; v1 = w1 * sc;
.LBB0_546:
	s_and_b64 vcc, exec, s[98:99]
	s_cbranch_vccnz .Lp2r_pf_8
	global_load_dwordx4 v[90:93], v[88:89], off
	global_load_dwordx4 v[136:139], v[88:89], off offset:16
	s_waitcnt vmcnt(0) lgkmcnt(0)
	s_branch .Lp2r_done_8
.Lp2r_pf_8:
	s_waitcnt lgkmcnt(0)
	v_mov_b64_e32 v[90:91], v[186:187]
	v_mov_b64_e32 v[92:93], v[188:189]
	v_mov_b64_e32 v[136:137], v[190:191]
	v_mov_b64_e32 v[138:139], v[192:193]
.Lp2r_done_8:
	v_pk_mul_f32 v[88:89], v[86:87], v[90:91] op_sel:[1,1] op_sel_hi:[0,1]
	v_mov_b32_e32 v0, v93
	v_pk_fma_f32 v[98:99], v[86:87], v[90:91], v[88:89] op_sel_hi:[1,0,1] neg_lo:[0,0,1] neg_hi:[0,0,1]
	v_pk_fma_f32 v[86:87], v[86:87], v[90:91], v[88:89] op_sel_hi:[1,0,1]
	v_pk_mul_f32 v[88:89], v[68:69], v[0:1] op_sel:[1,0] op_sel_hi:[0,0]
	v_pk_fma_f32 v[90:91], v[68:69], v[92:93], v[88:89] op_sel_hi:[1,0,1] neg_lo:[0,0,1] neg_hi:[0,0,1]
	v_pk_fma_f32 v[68:69], v[68:69], v[92:93], v[88:89] op_sel_hi:[1,0,1]
	v_pk_mul_f32 v[88:89], v[84:85], v[136:137] op_sel:[1,1] op_sel_hi:[0,1]
	v_mov_b32_e32 v0, v139
	v_pk_fma_f32 v[92:93], v[84:85], v[136:137], v[88:89] op_sel_hi:[1,0,1] neg_lo:[0,0,1] neg_hi:[0,0,1]
	v_pk_fma_f32 v[84:85], v[84:85], v[136:137], v[88:89] op_sel_hi:[1,0,1]
	v_pk_mul_f32 v[88:89], v[66:67], v[0:1] op_sel:[1,0] op_sel_hi:[0,0]
	v_pk_fma_f32 v[108:109], v[66:67], v[138:139], v[88:89] op_sel_hi:[1,0,1] neg_lo:[0,0,1] neg_hi:[0,0,1]
	v_pk_fma_f32 v[66:67], v[66:67], v[138:139], v[88:89] op_sel_hi:[1,0,1]
	v_mov_b32_e32 v91, v69
	v_mov_b32_e32 v68, v62
	v_mov_b32_e32 v69, v62
	v_mov_b32_e32 v99, v87
	v_mov_b32_e32 v109, v67
	v_mov_b32_e32 v93, v85
	v_pk_mul_f32 v[90:91], v[68:69], v[90:91]
	v_pk_mul_f32 v[88:89], v[62:63], v[98:99]
	v_pk_mul_f32 v[98:99], v[68:69], v[108:109]
	v_pk_mul_f32 v[92:93], v[62:63], v[92:93]

;     __device__ __forceinline__ void operator()(const f32x4 (&acc)[2][2][4][2], const Unit& u, int wr, int wc, int fr, int fq) const {
;     ...
;                     f32x4 v0 = acc[ai][bj][m][0] * rs + s0, v1 = acc[ai][bj][m][1] * rs + s1;
;                     if (mode == 1 || mode == 2) {
;                         const float* tp = (mode == 1) ? (ropA + ((size_t)row * 32 + ((col0 & 63) >> 1)) * 2) : (ropB + ((size_t)row * 16 + ((col0 - PC_KR) >> 1)) * 2);
;                         const f32x4 c0 = *(const f32x4*)tp, c1 = *(const f32x4*)(tp + 4);
;                         f32x4 w0, w1;
;                         w0[0] = v0[0] * c0[0] - v0[1] * c0[1]; w0[1] = v0[1] * c0[0] + v0[0] * c0[1];
;                         w0[2] = v0[2] * c0[2] - v0[3] * c0[3]; w0[3] = v0[3] * c0[2] + v0[2] * c0[3];
;                         w1[0] = v1[0] * c1[0] - v1[1] * c1[1]; w1[1] = v1[1] * c1[0] + v1[0] * c1[1];
;                         w1[2] = v1[2] * c1[2] - v1[3] * c1[3]; w1[3] = v1[3] * c1[2] + v1[2] * c1[3];
;                         v0 = w0 * sc; v1 = w1 * sc;
.LBB0_561:
	s_and_b64 vcc, exec, s[98:99]
	s_cbranch_vccnz .Lp2r_pf_9
	global_load_dwordx4 v[84:87], v[54:55], off
	global_load_dwordx4 v[88:91], v[54:55], off offset:16
	s_waitcnt vmcnt(0) lgkmcnt(0)
	s_branch .Lp2r_done_9
.Lp2r_pf_9:
	s_waitcnt lgkmcnt(0)
	v_mov_b64_e32 v[84:85], v[208:209]
	v_mov_b64_e32 v[86:87], v[210:211]
	v_mov_b64_e32 v[88:89], v[212:213]
	v_mov_b64_e32 v[90:91], v[214:215]
.Lp2r_done_9:
	v_mov_b32_e32 v0, v87
	v_pk_mul_f32 v[54:55], v[66:67], v[84:85] op_sel:[1,1] op_sel_hi:[0,1]
	v_pk_mul_f32 v[58:59], v[60:61], v[0:1] op_sel:[1,0] op_sel_hi:[0,0]
	v_pk_fma_f32 v[92:93], v[66:67], v[84:85], v[54:55] op_sel_hi:[1,0,1] neg_lo:[0,0,1] neg_hi:[0,0,1]
	v_pk_fma_f32 v[54:55], v[66:67], v[84:85], v[54:55] op_sel_hi:[1,0,1]
	v_pk_fma_f32 v[66:67], v[60:61], v[86:87], v[58:59] op_sel_hi:[1,0,1] neg_lo:[0,0,1] neg_hi:[0,0,1]
	v_pk_fma_f32 v[58:59], v[60:61], v[86:87], v[58:59] op_sel_hi:[1,0,1]
	v_pk_mul_f32 v[60:61], v[68:69], v[88:89] op_sel:[1,1] op_sel_hi:[0,1]
	v_mov_b32_e32 v0, v91
	v_pk_fma_f32 v[84:85], v[68:69], v[88:89], v[60:61] op_sel_hi:[1,0,1] neg_lo:[0,0,1] neg_hi:[0,0,1]
	v_pk_fma_f32 v[60:61], v[68:69], v[88:89], v[60:61] op_sel_hi:[1,0,1]
	v_pk_mul_f32 v[68:69], v[56:57], v[0:1] op_sel:[1,0] op_sel_hi:[0,0]
	v_pk_fma_f32 v[86:87], v[56:57], v[90:91], v[68:69] op_sel_hi:[1,0,1] neg_lo:[0,0,1] neg_hi:[0,0,1]
	v_pk_fma_f32 v[56:57], v[56:57], v[90:91], v[68:69] op_sel_hi:[1,0,1]
	v_mov_b32_e32 v67, v59
	v_mov_b32_e32 v68, v62
	v_mov_b32_e32 v69, v62
	v_mov_b32_e32 v93, v55
	v_mov_b32_e32 v87, v57
	v_mov_b32_e32 v85, v61
	v_pk_mul_f32 v[58:59], v[68:69], v[66:67]
	v_pk_mul_f32 v[54:55], v[62:63], v[92:93]
	v_pk_mul_f32 v[86:87], v[68:69], v[86:87]
	v_pk_mul_f32 v[84:85], v[62:63], v[84:85]
	v_cndmask_b32_e64 v0, 0, 1, s[40:41]
	v_cmp_ne_u32_e64 s[16:17], 1, v0
	s_andn2_b64 vcc, exec, s[40:41]
	s_cbranch_vccnz .LBB0_565

;     __device__ __forceinline__ void operator()(const f32x4 (&acc)[2][2][4][2], const Unit& u, int wr, int wc, int fr, int fq) const {
;     ...
;                     f32x4 v0 = acc[ai][bj][m][0] * rs + s0, v1 = acc[ai][bj][m][1] * rs + s1;
;                     if (mode == 1 || mode == 2) {
;                         const float* tp = (mode == 1) ? (ropA + ((size_t)row * 32 + ((col0 & 63) >> 1)) * 2) : (ropB + ((size_t)row * 16 + ((col0 - PC_KR) >> 1)) * 2);
;                         const f32x4 c0 = *(const f32x4*)tp, c1 = *(const f32x4*)(tp + 4);
;                         f32x4 w0, w1;
;                         w0[0] = v0[0] * c0[0] - v0[1] * c0[1]; w0[1] = v0[1] * c0[0] + v0[0] * c0[1];
;                         w0[2] = v0[2] * c0[2] - v0[3] * c0[3]; w0[3] = v0[3] * c0[2] + v0[2] * c0[3];
;                         w1[0] = v1[0] * c1[0] - v1[1] * c1[1]; w1[1] = v1[1] * c1[0] + v1[0] * c1[1];
;                         w1[2] = v1[2] * c1[2] - v1[3] * c1[3]; w1[3] = v1[3] * c1[2] + v1[2] * c1[3];
;                         v0 = w0 * sc; v1 = w1 * sc;
.LBB0_575:
	s_and_b64 vcc, exec, s[98:99]
	s_cbranch_vccnz .Lp2r_pf_10
	global_load_dwordx4 v[58:61], v[46:47], off
	global_load_dwordx4 v[66:69], v[46:47], off offset:16
	s_waitcnt vmcnt(0) lgkmcnt(0)
	s_branch .Lp2r_done_10
.Lp2r_pf_10:
	s_waitcnt lgkmcnt(0)
	v_mov_b64_e32 v[58:59], v[216:217]
	v_mov_b64_e32 v[60:61], v[218:219]
	v_mov_b64_e32 v[66:67], v[228:229]
	v_mov_b64_e32 v[68:69], v[230:231]
.Lp2r_done_10:
	v_mov_b32_e32 v0, v61
	v_pk_mul_f32 v[46:47], v[54:55], v[58:59] op_sel:[1,1] op_sel_hi:[0,1]
	v_pk_mul_f32 v[50:51], v[52:53], v[0:1] op_sel:[1,0] op_sel_hi:[0,0]
	v_pk_fma_f32 v[84:85], v[54:55], v[58:59], v[46:47] op_sel_hi:[1,0,1] neg_lo:[0,0,1] neg_hi:[0,0,1]
	v_pk_fma_f32 v[46:47], v[54:55], v[58:59], v[46:47] op_sel_hi:[1,0,1]
	v_pk_fma_f32 v[54:55], v[52:53], v[60:61], v[50:51] op_sel_hi:[1,0,1] neg_lo:[0,0,1] neg_hi:[0,0,1]
	v_pk_fma_f32 v[50:51], v[52:53], v[60:61], v[50:51] op_sel_hi:[1,0,1]
	v_pk_mul_f32 v[52:53], v[56:57], v[66:67] op_sel:[1,1] op_sel_hi:[0,1]
	v_mov_b32_e32 v0, v69
	v_pk_fma_f32 v[58:59], v[56:57], v[66:67], v[52:53] op_sel_hi:[1,0,1] neg_lo:[0,0,1] neg_hi:[0,0,1]
	v_pk_fma_f32 v[52:53], v[56:57], v[66:67], v[52:53] op_sel_hi:[1,0,1]
	v_pk_mul_f32 v[56:57], v[48:49], v[0:1] op_sel:[1,0] op_sel_hi:[0,0]
	v_pk_fma_f32 v[60:61], v[48:49], v[68:69], v[56:57] op_sel_hi:[1,0,1] neg_lo:[0,0,1] neg_hi:[0,0,1]
	v_pk_fma_f32 v[48:49], v[48:49], v[68:69], v[56:57] op_sel_hi:[1,0,1]
	v_mov_b32_e32 v55, v51
	v_mov_b32_e32 v56, v62
	v_mov_b32_e32 v57, v62
	v_mov_b32_e32 v85, v47
	v_mov_b32_e32 v61, v49
	v_mov_b32_e32 v59, v53
	v_pk_mul_f32 v[50:51], v[56:57], v[54:55]
	v_pk_mul_f32 v[46:47], v[62:63], v[84:85]
	v_pk_mul_f32 v[60:61], v[56:57], v[60:61]
	v_pk_mul_f32 v[58:59], v[62:63], v[58:59]
	s_and_b64 vcc, exec, s[16:17]
	s_cbranch_vccnz .LBB0_579

;     __device__ __forceinline__ void operator()(const f32x4 (&acc)[2][2][4][2], const Unit& u, int wr, int wc, int fr, int fq) const {
;     ...
;                     f32x4 v0 = acc[ai][bj][m][0] * rs + s0, v1 = acc[ai][bj][m][1] * rs + s1;
;                     if (mode == 1 || mode == 2) {
;                         const float* tp = (mode == 1) ? (ropA + ((size_t)row * 32 + ((col0 & 63) >> 1)) * 2) : (ropB + ((size_t)row * 16 + ((col0 - PC_KR) >> 1)) * 2);
;                         const f32x4 c0 = *(const f32x4*)tp, c1 = *(const f32x4*)(tp + 4);
;                         f32x4 w0, w1;
;                         w0[0] = v0[0] * c0[0] - v0[1] * c0[1]; w0[1] = v0[1] * c0[0] + v0[0] * c0[1];
;                         w0[2] = v0[2] * c0[2] - v0[3] * c0[3]; w0[3] = v0[3] * c0[2] + v0[2] * c0[3];
;                         w1[0] = v1[0] * c1[0] - v1[1] * c1[1]; w1[1] = v1[1] * c1[0] + v1[0] * c1[1];
;                         w1[2] = v1[2] * c1[2] - v1[3] * c1[3]; w1[3] = v1[3] * c1[2] + v1[2] * c1[3];
;                         v0 = w0 * sc; v1 = w1 * sc;
.LBB0_589:
	s_and_b64 vcc, exec, s[98:99]
	s_cbranch_vccnz .Lp2r_pf_11
	global_load_dwordx4 v[50:53], v[38:39], off
	global_load_dwordx4 v[54:57], v[38:39], off offset:16
	s_waitcnt vmcnt(0) lgkmcnt(0)
	s_branch .Lp2r_done_11
.Lp2r_pf_11:
	s_waitcnt lgkmcnt(0)
	v_mov_b64_e32 v[50:51], v[232:233]
	v_mov_b64_e32 v[52:53], v[234:235]
	v_mov_b64_e32 v[54:55], v[236:237]
	v_mov_b64_e32 v[56:57], v[238:239]
	v_add_u32_e32 v250, 0x8000, v220
	global_load_dwordx4 v[240:243], v250, s[24:25]
	global_load_dwordx4 v[244:247], v250, s[24:25] offset:16
.Lp2r_done_11:
	v_mov_b32_e32 v0, v53
	v_pk_mul_f32 v[38:39], v[46:47], v[50:51] op_sel:[1,1] op_sel_hi:[0,1]
	v_pk_mul_f32 v[42:43], v[44:45], v[0:1] op_sel:[1,0] op_sel_hi:[0,0]
	v_pk_fma_f32 v[58:59], v[46:47], v[50:51], v[38:39] op_sel_hi:[1,0,1] neg_lo:[0,0,1] neg_hi:[0,0,1]
	v_pk_fma_f32 v[38:39], v[46:47], v[50:51], v[38:39] op_sel_hi:[1,0,1]
	v_pk_fma_f32 v[46:47], v[44:45], v[52:53], v[42:43] op_sel_hi:[1,0,1] neg_lo:[0,0,1] neg_hi:[0,0,1]
	v_pk_fma_f32 v[42:43], v[44:45], v[52:53], v[42:43] op_sel_hi:[1,0,1]
	v_pk_mul_f32 v[44:45], v[48:49], v[54:55] op_sel:[1,1] op_sel_hi:[0,1]
	v_mov_b32_e32 v0, v57
	v_pk_fma_f32 v[50:51], v[48:49], v[54:55], v[44:45] op_sel_hi:[1,0,1] neg_lo:[0,0,1] neg_hi:[0,0,1]
	v_pk_fma_f32 v[44:45], v[48:49], v[54:55], v[44:45] op_sel_hi:[1,0,1]
	v_pk_mul_f32 v[48:49], v[40:41], v[0:1] op_sel:[1,0] op_sel_hi:[0,0]
	v_pk_fma_f32 v[52:53], v[40:41], v[56:57], v[48:49] op_sel_hi:[1,0,1] neg_lo:[0,0,1] neg_hi:[0,0,1]
	v_pk_fma_f32 v[40:41], v[40:41], v[56:57], v[48:49] op_sel_hi:[1,0,1]
	v_mov_b32_e32 v47, v43
	v_mov_b32_e32 v48, v62
	v_mov_b32_e32 v49, v62
	v_mov_b32_e32 v59, v39
	v_mov_b32_e32 v53, v41
	v_mov_b32_e32 v51, v45
	v_pk_mul_f32 v[42:43], v[48:49], v[46:47]
	v_pk_mul_f32 v[38:39], v[62:63], v[58:59]
	v_pk_mul_f32 v[52:53], v[48:49], v[52:53]
	v_pk_mul_f32 v[50:51], v[62:63], v[50:51]
	s_and_b64 vcc, exec, s[16:17]
	s_cbranch_vccnz .LBB0_593

;     __device__ __forceinline__ void operator()(const f32x4 (&acc)[2][2][4][2], const Unit& u, int wr, int wc, int fr, int fq) const {
;     ...
;                     f32x4 v0 = acc[ai][bj][m][0] * rs + s0, v1 = acc[ai][bj][m][1] * rs + s1;
;                     if (mode == 1 || mode == 2) {
;                         const float* tp = (mode == 1) ? (ropA + ((size_t)row * 32 + ((col0 & 63) >> 1)) * 2) : (ropB + ((size_t)row * 16 + ((col0 - PC_KR) >> 1)) * 2);
;                         const f32x4 c0 = *(const f32x4*)tp, c1 = *(const f32x4*)(tp + 4);
;                         f32x4 w0, w1;
;                         w0[0] = v0[0] * c0[0] - v0[1] * c0[1]; w0[1] = v0[1] * c0[0] + v0[0] * c0[1];
;                         w0[2] = v0[2] * c0[2] - v0[3] * c0[3]; w0[3] = v0[3] * c0[2] + v0[2] * c0[3];
;                         w1[0] = v1[0] * c1[0] - v1[1] * c1[1]; w1[1] = v1[1] * c1[0] + v1[0] * c1[1];
;                         w1[2] = v1[2] * c1[2] - v1[3] * c1[3]; w1[3] = v1[3] * c1[2] + v1[2] * c1[3];
;                         v0 = w0 * sc; v1 = w1 * sc;
.LBB0_603:
	s_and_b64 vcc, exec, s[98:99]
	s_cbranch_vccnz .Lp2r_pf_12
	global_load_dwordx4 v[42:45], v[30:31], off
	s_nop 0
	global_load_dwordx4 v[30:33], v[30:31], off offset:16
	s_waitcnt vmcnt(0) lgkmcnt(0)
	s_branch .Lp2r_done_12
.Lp2r_pf_12:
	s_waitcnt vmcnt(1) lgkmcnt(0)
	v_mov_b64_e32 v[42:43], v[240:241]
	v_mov_b64_e32 v[44:45], v[242:243]
	v_mov_b64_e32 v[30:31], v[244:245]
	v_mov_b64_e32 v[32:33], v[246:247]
	v_add_u32_e32 v250, 0x9000, v220
	global_load_dwordx4 v[240:243], v250, s[24:25]
	global_load_dwordx4 v[244:247], v250, s[24:25] offset:16
.Lp2r_done_12:
	v_pk_mul_f32 v[46:47], v[38:39], v[42:43] op_sel:[1,1] op_sel_hi:[0,1]
	v_mov_b32_e32 v0, v45
	v_pk_fma_f32 v[48:49], v[38:39], v[42:43], v[46:47] op_sel_hi:[1,0,1] neg_lo:[0,0,1] neg_hi:[0,0,1]
	v_pk_fma_f32 v[38:39], v[38:39], v[42:43], v[46:47] op_sel_hi:[1,0,1]
	v_pk_mul_f32 v[42:43], v[36:37], v[0:1] op_sel:[1,0] op_sel_hi:[0,0]
	v_pk_fma_f32 v[46:47], v[36:37], v[44:45], v[42:43] op_sel_hi:[1,0,1] neg_lo:[0,0,1] neg_hi:[0,0,1]
	v_pk_fma_f32 v[36:37], v[36:37], v[44:45], v[42:43] op_sel_hi:[1,0,1]
	v_pk_mul_f32 v[42:43], v[40:41], v[30:31] op_sel:[1,1] op_sel_hi:[0,1]
	v_mov_b32_e32 v0, v33
	v_pk_fma_f32 v[50:51], v[40:41], v[30:31], v[42:43] op_sel_hi:[1,0,1] neg_lo:[0,0,1] neg_hi:[0,0,1]
	v_pk_fma_f32 v[40:41], v[40:41], v[30:31], v[42:43] op_sel_hi:[1,0,1]
	v_pk_mul_f32 v[30:31], v[34:35], v[0:1] op_sel:[1,0] op_sel_hi:[0,0]
	v_pk_fma_f32 v[42:43], v[34:35], v[32:33], v[30:31] op_sel_hi:[1,0,1] neg_lo:[0,0,1] neg_hi:[0,0,1]
	v_pk_fma_f32 v[34:35], v[34:35], v[32:33], v[30:31] op_sel_hi:[1,0,1]
	v_mov_b32_e32 v47, v37
	v_mov_b32_e32 v36, v62
	v_mov_b32_e32 v37, v62
	v_mov_b32_e32 v49, v39
	v_mov_b32_e32 v43, v35
	v_mov_b32_e32 v51, v41
	v_pk_mul_f32 v[32:33], v[36:37], v[46:47]
	v_pk_mul_f32 v[30:31], v[62:63], v[48:49]
	v_pk_mul_f32 v[44:45], v[36:37], v[42:43]
	v_pk_mul_f32 v[42:43], v[62:63], v[50:51]
	s_and_b64 vcc, exec, s[16:17]
	s_cbranch_vccnz .LBB0_607

;     __device__ __forceinline__ void operator()(const f32x4 (&acc)[2][2][4][2], const Unit& u, int wr, int wc, int fr, int fq) const {
;     ...
;                     f32x4 v0 = acc[ai][bj][m][0] * rs + s0, v1 = acc[ai][bj][m][1] * rs + s1;
;                     if (mode == 1 || mode == 2) {
;                         const float* tp = (mode == 1) ? (ropA + ((size_t)row * 32 + ((col0 & 63) >> 1)) * 2) : (ropB + ((size_t)row * 16 + ((col0 - PC_KR) >> 1)) * 2);
;                         const f32x4 c0 = *(const f32x4*)tp, c1 = *(const f32x4*)(tp + 4);
;                         f32x4 w0, w1;
;                         w0[0] = v0[0] * c0[0] - v0[1] * c0[1]; w0[1] = v0[1] * c0[0] + v0[0] * c0[1];
;                         w0[2] = v0[2] * c0[2] - v0[3] * c0[3]; w0[3] = v0[3] * c0[2] + v0[2] * c0[3];
;                         w1[0] = v1[0] * c1[0] - v1[1] * c1[1]; w1[1] = v1[1] * c1[0] + v1[0] * c1[1];
;                         w1[2] = v1[2] * c1[2] - v1[3] * c1[3]; w1[3] = v1[3] * c1[2] + v1[2] * c1[3];
;                         v0 = w0 * sc; v1 = w1 * sc;
.LBB0_617:
	s_waitcnt lgkmcnt(0)
	s_and_b64 vcc, exec, s[98:99]
	s_cbranch_vccnz .Lp2r_pf_13
	global_load_dwordx4 v[34:37], v[22:23], off
	global_load_dwordx4 v[38:41], v[22:23], off offset:16
	s_waitcnt vmcnt(0) lgkmcnt(0)
	s_branch .Lp2r_done_13
.Lp2r_pf_13:
	s_waitcnt vmcnt(1) lgkmcnt(0)
	v_mov_b64_e32 v[34:35], v[240:241]
	v_mov_b64_e32 v[36:37], v[242:243]
	v_mov_b64_e32 v[38:39], v[244:245]
	v_mov_b64_e32 v[40:41], v[246:247]
	v_add_u32_e32 v250, 0xa000, v220
	global_load_dwordx4 v[240:243], v250, s[24:25]
	global_load_dwordx4 v[244:247], v250, s[24:25] offset:16
.Lp2r_done_13:
	v_mov_b32_e32 v0, v37
	v_pk_mul_f32 v[22:23], v[30:31], v[34:35] op_sel:[1,1] op_sel_hi:[0,1]
	v_pk_mul_f32 v[26:27], v[28:29], v[0:1] op_sel:[1,0] op_sel_hi:[0,0]
	v_pk_fma_f32 v[42:43], v[30:31], v[34:35], v[22:23] op_sel_hi:[1,0,1] neg_lo:[0,0,1] neg_hi:[0,0,1]
	v_pk_fma_f32 v[22:23], v[30:31], v[34:35], v[22:23] op_sel_hi:[1,0,1]
	v_pk_fma_f32 v[30:31], v[28:29], v[36:37], v[26:27] op_sel_hi:[1,0,1] neg_lo:[0,0,1] neg_hi:[0,0,1]
	v_pk_fma_f32 v[26:27], v[28:29], v[36:37], v[26:27] op_sel_hi:[1,0,1]
	v_pk_mul_f32 v[28:29], v[32:33], v[38:39] op_sel:[1,1] op_sel_hi:[0,1]
	v_mov_b32_e32 v0, v41
	v_pk_fma_f32 v[34:35], v[32:33], v[38:39], v[28:29] op_sel_hi:[1,0,1] neg_lo:[0,0,1] neg_hi:[0,0,1]
	v_pk_fma_f32 v[28:29], v[32:33], v[38:39], v[28:29] op_sel_hi:[1,0,1]
	v_pk_mul_f32 v[32:33], v[24:25], v[0:1] op_sel:[1,0] op_sel_hi:[0,0]
	v_pk_fma_f32 v[36:37], v[24:25], v[40:41], v[32:33] op_sel_hi:[1,0,1] neg_lo:[0,0,1] neg_hi:[0,0,1]
	v_pk_fma_f32 v[24:25], v[24:25], v[40:41], v[32:33] op_sel_hi:[1,0,1]
	v_mov_b32_e32 v31, v27
	v_mov_b32_e32 v32, v62
	v_mov_b32_e32 v33, v62
	v_mov_b32_e32 v43, v23
	v_mov_b32_e32 v37, v25
	v_mov_b32_e32 v35, v29
	v_pk_mul_f32 v[26:27], v[32:33], v[30:31]
	v_pk_mul_f32 v[22:23], v[62:63], v[42:43]
	v_pk_mul_f32 v[36:37], v[32:33], v[36:37]
	v_pk_mul_f32 v[34:35], v[62:63], v[34:35]
	s_and_b64 vcc, exec, s[16:17]
	s_cbranch_vccnz .LBB0_621

;     __device__ __forceinline__ void operator()(const f32x4 (&acc)[2][2][4][2], const Unit& u, int wr, int wc, int fr, int fq) const {
;     ...
;                     f32x4 v0 = acc[ai][bj][m][0] * rs + s0, v1 = acc[ai][bj][m][1] * rs + s1;
;                     if (mode == 1 || mode == 2) {
;                         const float* tp = (mode == 1) ? (ropA + ((size_t)row * 32 + ((col0 & 63) >> 1)) * 2) : (ropB + ((size_t)row * 16 + ((col0 - PC_KR) >> 1)) * 2);
;                         const f32x4 c0 = *(const f32x4*)tp, c1 = *(const f32x4*)(tp + 4);
;                         f32x4 w0, w1;
;                         w0[0] = v0[0] * c0[0] - v0[1] * c0[1]; w0[1] = v0[1] * c0[0] + v0[0] * c0[1];
;                         w0[2] = v0[2] * c0[2] - v0[3] * c0[3]; w0[3] = v0[3] * c0[2] + v0[2] * c0[3];
;                         w1[0] = v1[0] * c1[0] - v1[1] * c1[1]; w1[1] = v1[1] * c1[0] + v1[0] * c1[1];
;                         w1[2] = v1[2] * c1[2] - v1[3] * c1[3]; w1[3] = v1[3] * c1[2] + v1[2] * c1[3];
;                         v0 = w0 * sc; v1 = w1 * sc;
.LBB0_631:
	s_and_b64 vcc, exec, s[98:99]
	s_cbranch_vccnz .Lp2r_pf_14
	global_load_dwordx4 v[26:29], v[10:11], off
	global_load_dwordx4 v[30:33], v[10:11], off offset:16
	s_waitcnt vmcnt(0) lgkmcnt(0)
	s_branch .Lp2r_done_14
.Lp2r_pf_14:
	s_waitcnt vmcnt(1) lgkmcnt(0)
	v_mov_b64_e32 v[26:27], v[240:241]
	v_mov_b64_e32 v[28:29], v[242:243]
	v_mov_b64_e32 v[30:31], v[244:245]
	v_mov_b64_e32 v[32:33], v[246:247]
	v_add_u32_e32 v250, 0xb000, v220
	global_load_dwordx4 v[240:243], v250, s[24:25]
	global_load_dwordx4 v[244:247], v250, s[24:25] offset:16
.Lp2r_done_14:
	v_mov_b32_e32 v0, v29
	v_pk_mul_f32 v[10:11], v[22:23], v[26:27] op_sel:[1,1] op_sel_hi:[0,1]
	v_pk_mul_f32 v[18:19], v[20:21], v[0:1] op_sel:[1,0] op_sel_hi:[0,0]
	v_pk_fma_f32 v[34:35], v[22:23], v[26:27], v[10:11] op_sel_hi:[1,0,1] neg_lo:[0,0,1] neg_hi:[0,0,1]
	v_pk_fma_f32 v[10:11], v[22:23], v[26:27], v[10:11] op_sel_hi:[1,0,1]
	v_pk_fma_f32 v[22:23], v[20:21], v[28:29], v[18:19] op_sel_hi:[1,0,1] neg_lo:[0,0,1] neg_hi:[0,0,1]
	v_pk_fma_f32 v[18:19], v[20:21], v[28:29], v[18:19] op_sel_hi:[1,0,1]
	v_pk_mul_f32 v[20:21], v[24:25], v[30:31] op_sel:[1,1] op_sel_hi:[0,1]
	v_mov_b32_e32 v0, v33
	v_pk_fma_f32 v[26:27], v[24:25], v[30:31], v[20:21] op_sel_hi:[1,0,1] neg_lo:[0,0,1] neg_hi:[0,0,1]
	v_pk_fma_f32 v[20:21], v[24:25], v[30:31], v[20:21] op_sel_hi:[1,0,1]
	v_pk_mul_f32 v[24:25], v[12:13], v[0:1] op_sel:[1,0] op_sel_hi:[0,0]
	v_pk_fma_f32 v[28:29], v[12:13], v[32:33], v[24:25] op_sel_hi:[1,0,1] neg_lo:[0,0,1] neg_hi:[0,0,1]
	v_pk_fma_f32 v[12:13], v[12:13], v[32:33], v[24:25] op_sel_hi:[1,0,1]
	v_mov_b32_e32 v23, v19
	v_mov_b32_e32 v24, v62
	v_mov_b32_e32 v25, v62
	v_mov_b32_e32 v35, v11
	v_mov_b32_e32 v29, v13
	v_mov_b32_e32 v27, v21
	v_pk_mul_f32 v[18:19], v[24:25], v[22:23]
	v_pk_mul_f32 v[10:11], v[62:63], v[34:35]
	v_pk_mul_f32 v[28:29], v[24:25], v[28:29]
	v_pk_mul_f32 v[26:27], v[62:63], v[26:27]
	s_and_b64 vcc, exec, s[16:17]
	s_cbranch_vccnz .LBB0_635

;     __device__ __forceinline__ void operator()(const f32x4 (&acc)[2][2][4][2], const Unit& u, int wr, int wc, int fr, int fq) const {
;     ...
;                     f32x4 v0 = acc[ai][bj][m][0] * rs + s0, v1 = acc[ai][bj][m][1] * rs + s1;
;                     if (mode == 1 || mode == 2) {
;                         const float* tp = (mode == 1) ? (ropA + ((size_t)row * 32 + ((col0 & 63) >> 1)) * 2) : (ropB + ((size_t)row * 16 + ((col0 - PC_KR) >> 1)) * 2);
;                         const f32x4 c0 = *(const f32x4*)tp, c1 = *(const f32x4*)(tp + 4);
;                         f32x4 w0, w1;
;                         w0[0] = v0[0] * c0[0] - v0[1] * c0[1]; w0[1] = v0[1] * c0[0] + v0[0] * c0[1];
;                         w0[2] = v0[2] * c0[2] - v0[3] * c0[3]; w0[3] = v0[3] * c0[2] + v0[2] * c0[3];
;                         w1[0] = v1[0] * c1[0] - v1[1] * c1[1]; w1[1] = v1[1] * c1[0] + v1[0] * c1[1];
;                         w1[2] = v1[2] * c1[2] - v1[3] * c1[3]; w1[3] = v1[3] * c1[2] + v1[2] * c1[3];
;                         v0 = w0 * sc; v1 = w1 * sc;
.LBB0_645:
	s_and_b64 vcc, exec, s[98:99]
	s_cbranch_vccnz .Lp2r_pf_15
	global_load_dwordx4 v[18:21], v[2:3], off
	global_load_dwordx4 v[22:25], v[2:3], off offset:16
	s_waitcnt vmcnt(0) lgkmcnt(0)
	s_branch .Lp2r_done_15
.Lp2r_pf_15:
	s_waitcnt vmcnt(1) lgkmcnt(0)
	v_mov_b64_e32 v[18:19], v[240:241]
	v_mov_b64_e32 v[20:21], v[242:243]
	v_mov_b64_e32 v[22:23], v[244:245]
	v_mov_b64_e32 v[24:25], v[246:247]
.Lp2r_done_15:
	v_mov_b32_e32 v0, v21
	v_pk_mul_f32 v[2:3], v[10:11], v[18:19] op_sel:[1,1] op_sel_hi:[0,1]
	v_pk_mul_f32 v[6:7], v[8:9], v[0:1] op_sel:[1,0] op_sel_hi:[0,0]
	v_pk_fma_f32 v[26:27], v[10:11], v[18:19], v[2:3] op_sel_hi:[1,0,1] neg_lo:[0,0,1] neg_hi:[0,0,1]
	v_pk_fma_f32 v[2:3], v[10:11], v[18:19], v[2:3] op_sel_hi:[1,0,1]
	v_pk_fma_f32 v[10:11], v[8:9], v[20:21], v[6:7] op_sel_hi:[1,0,1] neg_lo:[0,0,1] neg_hi:[0,0,1]
	v_pk_fma_f32 v[6:7], v[8:9], v[20:21], v[6:7] op_sel_hi:[1,0,1]
	v_pk_mul_f32 v[8:9], v[12:13], v[22:23] op_sel:[1,1] op_sel_hi:[0,1]
	v_mov_b32_e32 v0, v25
	v_pk_fma_f32 v[18:19], v[12:13], v[22:23], v[8:9] op_sel_hi:[1,0,1] neg_lo:[0,0,1] neg_hi:[0,0,1]
	v_pk_fma_f32 v[8:9], v[12:13], v[22:23], v[8:9] op_sel_hi:[1,0,1]
	v_pk_mul_f32 v[12:13], v[4:5], v[0:1] op_sel:[1,0] op_sel_hi:[0,0]
	v_pk_fma_f32 v[20:21], v[4:5], v[24:25], v[12:13] op_sel_hi:[1,0,1] neg_lo:[0,0,1] neg_hi:[0,0,1]
	v_pk_fma_f32 v[4:5], v[4:5], v[24:25], v[12:13] op_sel_hi:[1,0,1]
	v_mov_b32_e32 v11, v7
	v_mov_b32_e32 v12, v62
	v_mov_b32_e32 v13, v62
	v_mov_b32_e32 v27, v3
	v_mov_b32_e32 v21, v5
	v_mov_b32_e32 v19, v9
	v_pk_mul_f32 v[6:7], v[12:13], v[10:11]
	v_pk_mul_f32 v[2:3], v[62:63], v[26:27]
	v_pk_mul_f32 v[20:21], v[12:13], v[20:21]
	v_pk_mul_f32 v[18:19], v[62:63], v[18:19]
	s_and_b64 vcc, exec, s[16:17]
	s_cbranch_vccnz .LBB0_649
